# P4 and P8 epilogues: lane-permuted stores software-pipelined too (alternating data quad / address pair), on top of v58
# speedup vs baseline: 1.0051x; 1.0051x over previous
.LBB0_597:
	v_and_b32_e32 v165, 3, v174
	v_lshrrev_b32_e32 v170, 2, v174
	v_lshlrev_b32_e32 v164, 6, v165
	v_and_or_b32 v164, v174, 60, v164
	v_and_b32_e32 v171, 15, v174
	v_sub_u32_e32 v170, v170, v171
	v_lshrrev_b32_e32 v171, 4, v174
	v_sub_u32_e32 v165, v165, v171
	v_mul_i32_i24_e32 v170, 0x200, v170
	v_lshl_add_u32 v166, v165, 4, v170
	v_ashrrev_i32_e32 v167, 31, v166
	s_add_i32 s2, s2, -1
	s_lshl_b64 s[28:29], s[2:3], 17
	v_lshl_add_u64 v[148:149], v[140:141], 0, s[28:29]
	v_cvt_pk_bf16_f32 v152, v126, v127
	v_cvt_pk_bf16_f32 v153, v128, v129
	v_cvt_pk_bf16_f32 v154, v122, v123
	v_cvt_pk_bf16_f32 v155, v124, v125
	s_movk_i32 s2, 0x2000
	ds_bpermute_b32 v152, v164, v152
	ds_bpermute_b32 v153, v164, v153
	ds_bpermute_b32 v154, v164, v154
	ds_bpermute_b32 v155, v164, v155
	v_lshl_add_u64 v[168:169], v[166:167], 0, v[148:149]
	v_add_co_u32_e32 v156, vcc, s2, v148
	s_nop 0
	v_cvt_pk_bf16_f32 v176, v118, v119
	v_cvt_pk_bf16_f32 v177, v120, v121
	v_cvt_pk_bf16_f32 v178, v114, v115
	v_cvt_pk_bf16_f32 v179, v116, v117
	ds_bpermute_b32 v176, v164, v176
	ds_bpermute_b32 v177, v164, v177
	ds_bpermute_b32 v178, v164, v178
	ds_bpermute_b32 v179, v164, v179
	v_lshl_add_u64 v[180:181], v[166:167], 0, v[148:149]
	s_waitcnt lgkmcnt(4)
	global_store_dwordx4 v[168:169], v[152:155], off
	v_addc_co_u32_e32 v157, vcc, 0, v149, vcc
	s_nop 0
	v_cvt_pk_bf16_f32 v152, v110, v111
	v_cvt_pk_bf16_f32 v153, v112, v113
	v_cvt_pk_bf16_f32 v154, v106, v107
	v_cvt_pk_bf16_f32 v155, v108, v109
	s_movk_i32 s2, 0x4000
	ds_bpermute_b32 v152, v164, v152
	ds_bpermute_b32 v153, v164, v153
	ds_bpermute_b32 v154, v164, v154
	ds_bpermute_b32 v155, v164, v155
	v_lshl_add_u64 v[168:169], v[166:167], 0, v[156:157]
	s_waitcnt lgkmcnt(4)
	global_store_dwordx4 v[180:181], v[176:179], off offset:256
	s_mov_b64 s[28:29], 0
	s_nop 0
	v_cvt_pk_bf16_f32 v176, v102, v103
	v_cvt_pk_bf16_f32 v177, v104, v105
	v_cvt_pk_bf16_f32 v178, v98, v99
	v_cvt_pk_bf16_f32 v179, v100, v101
	ds_bpermute_b32 v176, v164, v176
	ds_bpermute_b32 v177, v164, v177
	ds_bpermute_b32 v178, v164, v178
	ds_bpermute_b32 v179, v164, v179
	v_lshl_add_u64 v[180:181], v[166:167], 0, v[156:157]
	s_waitcnt lgkmcnt(4)
	global_store_dwordx4 v[168:169], v[152:155], off
	v_add_co_u32_e32 v156, vcc, s2, v148
	s_nop 0
	v_cvt_pk_bf16_f32 v152, v94, v95
	v_cvt_pk_bf16_f32 v153, v96, v97
	v_cvt_pk_bf16_f32 v154, v90, v91
	v_cvt_pk_bf16_f32 v155, v92, v93
	s_nop 0
	v_addc_co_u32_e32 v157, vcc, 0, v149, vcc
	s_movk_i32 s2, 0x6000
	ds_bpermute_b32 v152, v164, v152
	ds_bpermute_b32 v153, v164, v153
	ds_bpermute_b32 v154, v164, v154
	ds_bpermute_b32 v155, v164, v155
	v_lshl_add_u64 v[168:169], v[166:167], 0, v[156:157]
	s_waitcnt lgkmcnt(4)
	global_store_dwordx4 v[180:181], v[176:179], off offset:256
	s_nop 1
	v_cvt_pk_bf16_f32 v176, v86, v87
	v_cvt_pk_bf16_f32 v177, v88, v89
	v_cvt_pk_bf16_f32 v178, v82, v83
	v_cvt_pk_bf16_f32 v179, v84, v85
	ds_bpermute_b32 v176, v164, v176
	ds_bpermute_b32 v177, v164, v177
	ds_bpermute_b32 v178, v164, v178
	ds_bpermute_b32 v179, v164, v179
	v_lshl_add_u64 v[180:181], v[166:167], 0, v[156:157]
	s_waitcnt lgkmcnt(4)
	global_store_dwordx4 v[168:169], v[152:155], off
	v_add_co_u32_e32 v156, vcc, s2, v148
	s_nop 0
	v_cvt_pk_bf16_f32 v152, v78, v79
	v_cvt_pk_bf16_f32 v153, v80, v81
	v_cvt_pk_bf16_f32 v154, v74, v75
	v_cvt_pk_bf16_f32 v155, v76, v77
	s_nop 0
	v_addc_co_u32_e32 v157, vcc, 0, v149, vcc
	s_mov_b32 s2, 0x10000
	ds_bpermute_b32 v152, v164, v152
	ds_bpermute_b32 v153, v164, v153
	ds_bpermute_b32 v154, v164, v154
	ds_bpermute_b32 v155, v164, v155
	v_lshl_add_u64 v[168:169], v[166:167], 0, v[156:157]
	s_waitcnt lgkmcnt(4)
	global_store_dwordx4 v[180:181], v[176:179], off offset:256
	s_nop 1
	v_cvt_pk_bf16_f32 v176, v70, v71
	v_cvt_pk_bf16_f32 v177, v72, v73
	v_cvt_pk_bf16_f32 v178, v66, v67
	v_cvt_pk_bf16_f32 v179, v68, v69
	ds_bpermute_b32 v176, v164, v176
	ds_bpermute_b32 v177, v164, v177
	ds_bpermute_b32 v178, v164, v178
	ds_bpermute_b32 v179, v164, v179
	v_lshl_add_u64 v[180:181], v[166:167], 0, v[156:157]
	s_waitcnt lgkmcnt(4)
	global_store_dwordx4 v[168:169], v[152:155], off
	v_add_co_u32_e32 v156, vcc, s2, v148
	s_nop 0
	v_cvt_pk_bf16_f32 v152, v62, v63
	v_cvt_pk_bf16_f32 v153, v64, v65
	v_cvt_pk_bf16_f32 v154, v58, v59
	v_cvt_pk_bf16_f32 v155, v60, v61
	s_nop 0
	v_addc_co_u32_e32 v157, vcc, 0, v149, vcc
	s_mov_b32 s2, 0x12000
	ds_bpermute_b32 v152, v164, v152
	ds_bpermute_b32 v153, v164, v153
	ds_bpermute_b32 v154, v164, v154
	ds_bpermute_b32 v155, v164, v155
	v_lshl_add_u64 v[168:169], v[166:167], 0, v[156:157]
	s_waitcnt lgkmcnt(4)
	global_store_dwordx4 v[180:181], v[176:179], off offset:256
	s_nop 1
	v_cvt_pk_bf16_f32 v176, v54, v55
	v_cvt_pk_bf16_f32 v177, v56, v57
	v_cvt_pk_bf16_f32 v178, v50, v51
	v_cvt_pk_bf16_f32 v179, v52, v53
	ds_bpermute_b32 v176, v164, v176
	ds_bpermute_b32 v177, v164, v177
	ds_bpermute_b32 v178, v164, v178
	ds_bpermute_b32 v179, v164, v179
	v_lshl_add_u64 v[180:181], v[166:167], 0, v[156:157]
	s_waitcnt lgkmcnt(4)
	global_store_dwordx4 v[168:169], v[152:155], off
	v_add_co_u32_e32 v156, vcc, s2, v148
	s_nop 0
	v_cvt_pk_bf16_f32 v152, v46, v47
	v_cvt_pk_bf16_f32 v153, v48, v49
	v_cvt_pk_bf16_f32 v154, v42, v43
	v_cvt_pk_bf16_f32 v155, v44, v45
	s_nop 0
	v_addc_co_u32_e32 v157, vcc, 0, v149, vcc
	s_mov_b32 s2, 0x14000
	ds_bpermute_b32 v152, v164, v152
	ds_bpermute_b32 v153, v164, v153
	ds_bpermute_b32 v154, v164, v154
	ds_bpermute_b32 v155, v164, v155
	v_lshl_add_u64 v[168:169], v[166:167], 0, v[156:157]
	s_waitcnt lgkmcnt(4)
	global_store_dwordx4 v[180:181], v[176:179], off offset:256
	s_nop 1
	v_cvt_pk_bf16_f32 v176, v38, v39
	v_cvt_pk_bf16_f32 v177, v40, v41
	v_cvt_pk_bf16_f32 v178, v34, v35
	v_cvt_pk_bf16_f32 v179, v36, v37
	ds_bpermute_b32 v176, v164, v176
	ds_bpermute_b32 v177, v164, v177
	ds_bpermute_b32 v178, v164, v178
	ds_bpermute_b32 v179, v164, v179
	v_lshl_add_u64 v[180:181], v[166:167], 0, v[156:157]
	s_waitcnt lgkmcnt(4)
	global_store_dwordx4 v[168:169], v[152:155], off
	v_add_co_u32_e32 v156, vcc, s2, v148
	s_nop 0
	v_cvt_pk_bf16_f32 v152, v30, v31
	v_cvt_pk_bf16_f32 v153, v32, v33
	v_cvt_pk_bf16_f32 v154, v26, v27
	v_cvt_pk_bf16_f32 v155, v28, v29
	s_nop 0
	v_addc_co_u32_e32 v157, vcc, 0, v149, vcc
	s_mov_b32 s2, 0x16000
	ds_bpermute_b32 v152, v164, v152
	ds_bpermute_b32 v153, v164, v153
	ds_bpermute_b32 v154, v164, v154
	ds_bpermute_b32 v155, v164, v155
	v_lshl_add_u64 v[168:169], v[166:167], 0, v[156:157]
	s_waitcnt lgkmcnt(4)
	global_store_dwordx4 v[180:181], v[176:179], off offset:256
	v_add_co_u32_e32 v148, vcc, s2, v148
	s_nop 0
	v_cvt_pk_bf16_f32 v176, v22, v23
	v_cvt_pk_bf16_f32 v177, v24, v25
	v_cvt_pk_bf16_f32 v178, v18, v19
	v_cvt_pk_bf16_f32 v179, v20, v21
	ds_bpermute_b32 v176, v164, v176
	ds_bpermute_b32 v177, v164, v177
	ds_bpermute_b32 v178, v164, v178
	ds_bpermute_b32 v179, v164, v179
	v_lshl_add_u64 v[180:181], v[166:167], 0, v[156:157]
	s_waitcnt lgkmcnt(4)
	global_store_dwordx4 v[168:169], v[152:155], off
	v_addc_co_u32_e32 v149, vcc, 0, v149, vcc
	s_nop 0
	v_cvt_pk_bf16_f32 v152, v14, v15
	v_cvt_pk_bf16_f32 v153, v16, v17
	v_cvt_pk_bf16_f32 v154, v10, v11
	v_cvt_pk_bf16_f32 v155, v12, v13
	ds_bpermute_b32 v152, v164, v152
	ds_bpermute_b32 v153, v164, v153
	ds_bpermute_b32 v154, v164, v154
	ds_bpermute_b32 v155, v164, v155
	v_lshl_add_u64 v[168:169], v[166:167], 0, v[148:149]
	s_waitcnt lgkmcnt(4)
	global_store_dwordx4 v[180:181], v[176:179], off offset:256
	s_nop 1
	v_cvt_pk_bf16_f32 v176, v6, v7
	v_cvt_pk_bf16_f32 v177, v8, v9
	v_cvt_pk_bf16_f32 v178, v2, v3
	v_cvt_pk_bf16_f32 v179, v4, v5
	ds_bpermute_b32 v176, v164, v176
	ds_bpermute_b32 v177, v164, v177
	ds_bpermute_b32 v178, v164, v178
	ds_bpermute_b32 v179, v164, v179
	v_lshl_add_u64 v[180:181], v[166:167], 0, v[148:149]
	s_waitcnt lgkmcnt(4)
	global_store_dwordx4 v[168:169], v[152:155], off
	s_waitcnt lgkmcnt(0)
	global_store_dwordx4 v[180:181], v[176:179], off offset:256
.LBB0_598:
	s_andn2_b64 vcc, exec, s[28:29]
	s_cbranch_vccnz .LBB0_588
	v_and_b32_e32 v165, 3, v174
	v_lshrrev_b32_e32 v170, 2, v174
	v_lshlrev_b32_e32 v164, 6, v165
	v_and_or_b32 v164, v174, 60, v164
	v_and_b32_e32 v171, 15, v174
	v_sub_u32_e32 v170, v170, v171
	v_lshrrev_b32_e32 v171, 4, v174
	v_sub_u32_e32 v165, v165, v171
	v_mul_i32_i24_e32 v170, 0x2000, v170
	v_lshl_add_u32 v166, v165, 4, v170
	v_ashrrev_i32_e32 v167, 31, v166
	v_lshl_add_u32 v152, s18, 8, v138
	v_lshl_or_b32 v148, s16, 8, v139
	v_ashrrev_i32_e32 v153, 31, v152
	v_ashrrev_i32_e32 v149, 31, v148
	v_lshlrev_b64 v[154:155], 13, v[152:153]
	v_lshl_add_u64 v[154:155], s[4:5], 0, v[154:155]
	v_lshlrev_b64 v[156:157], 1, v[148:149]
	v_lshl_add_u64 v[148:149], v[154:155], 0, v[156:157]
	v_cvt_pk_bf16_f32 v126, v126, v127
	v_cvt_pk_bf16_f32 v127, v128, v129
	v_cvt_pk_bf16_f32 v128, v122, v123
	v_cvt_pk_bf16_f32 v129, v124, v125
	ds_bpermute_b32 v126, v164, v126
	ds_bpermute_b32 v127, v164, v127
	ds_bpermute_b32 v128, v164, v128
	ds_bpermute_b32 v129, v164, v129
	v_lshl_add_u64 v[168:169], v[166:167], 0, v[148:149]
	v_cvt_pk_bf16_f32 v118, v118, v119
	v_cvt_pk_bf16_f32 v119, v120, v121
	v_cvt_pk_bf16_f32 v120, v114, v115
	v_or_b32_e32 v114, 16, v152
	v_ashrrev_i32_e32 v115, 31, v114
	v_lshlrev_b64 v[114:115], 13, v[114:115]
	v_lshl_add_u64 v[114:115], s[4:5], 0, v[114:115]
	v_lshl_add_u64 v[114:115], v[114:115], 0, v[156:157]
	v_cvt_pk_bf16_f32 v121, v116, v117
	ds_bpermute_b32 v118, v164, v118
	ds_bpermute_b32 v119, v164, v119
	ds_bpermute_b32 v120, v164, v120
	ds_bpermute_b32 v121, v164, v121
	v_lshl_add_u64 v[180:181], v[166:167], 0, v[148:149]
	s_waitcnt lgkmcnt(4)
	global_store_dwordx4 v[168:169], v[126:129], off
	v_cvt_pk_bf16_f32 v110, v110, v111
	v_cvt_pk_bf16_f32 v111, v112, v113
	v_cvt_pk_bf16_f32 v112, v106, v107
	v_cvt_pk_bf16_f32 v113, v108, v109
	ds_bpermute_b32 v110, v164, v110
	ds_bpermute_b32 v111, v164, v111
	ds_bpermute_b32 v112, v164, v112
	ds_bpermute_b32 v113, v164, v113
	v_lshl_add_u64 v[168:169], v[166:167], 0, v[114:115]
	s_waitcnt lgkmcnt(4)
	global_store_dwordx4 v[180:181], v[118:121], off offset:256
	v_cvt_pk_bf16_f32 v102, v102, v103
	v_cvt_pk_bf16_f32 v103, v104, v105
	v_cvt_pk_bf16_f32 v104, v98, v99
	v_or_b32_e32 v98, 32, v152
	v_ashrrev_i32_e32 v99, 31, v98
	v_lshlrev_b64 v[98:99], 13, v[98:99]
	v_lshl_add_u64 v[98:99], s[4:5], 0, v[98:99]
	v_lshl_add_u64 v[98:99], v[98:99], 0, v[156:157]
	v_cvt_pk_bf16_f32 v105, v100, v101
	ds_bpermute_b32 v102, v164, v102
	ds_bpermute_b32 v103, v164, v103
	ds_bpermute_b32 v104, v164, v104
	ds_bpermute_b32 v105, v164, v105
	v_lshl_add_u64 v[180:181], v[166:167], 0, v[114:115]
	s_waitcnt lgkmcnt(4)
	global_store_dwordx4 v[168:169], v[110:113], off
	v_cvt_pk_bf16_f32 v94, v94, v95
	v_cvt_pk_bf16_f32 v95, v96, v97
	v_cvt_pk_bf16_f32 v96, v90, v91
	v_cvt_pk_bf16_f32 v97, v92, v93
	ds_bpermute_b32 v94, v164, v94
	ds_bpermute_b32 v95, v164, v95
	ds_bpermute_b32 v96, v164, v96
	ds_bpermute_b32 v97, v164, v97
	v_lshl_add_u64 v[168:169], v[166:167], 0, v[98:99]
	s_waitcnt lgkmcnt(4)
	global_store_dwordx4 v[180:181], v[102:105], off offset:256
	v_cvt_pk_bf16_f32 v86, v86, v87
	v_cvt_pk_bf16_f32 v87, v88, v89
	v_cvt_pk_bf16_f32 v88, v82, v83
	v_or_b32_e32 v82, 48, v152
	v_ashrrev_i32_e32 v83, 31, v82
	v_lshlrev_b64 v[82:83], 13, v[82:83]
	v_lshl_add_u64 v[82:83], s[4:5], 0, v[82:83]
	v_lshl_add_u64 v[82:83], v[82:83], 0, v[156:157]
	s_mov_b32 s2, 0x100000
	v_cvt_pk_bf16_f32 v89, v84, v85
	ds_bpermute_b32 v86, v164, v86
	ds_bpermute_b32 v87, v164, v87
	ds_bpermute_b32 v88, v164, v88
	ds_bpermute_b32 v89, v164, v89
	v_lshl_add_u64 v[180:181], v[166:167], 0, v[98:99]
	s_waitcnt lgkmcnt(4)
	global_store_dwordx4 v[168:169], v[94:97], off
	v_cvt_pk_bf16_f32 v78, v78, v79
	v_cvt_pk_bf16_f32 v79, v80, v81
	v_cvt_pk_bf16_f32 v80, v74, v75
	v_cvt_pk_bf16_f32 v81, v76, v77
	ds_bpermute_b32 v78, v164, v78
	ds_bpermute_b32 v79, v164, v79
	ds_bpermute_b32 v80, v164, v80
	ds_bpermute_b32 v81, v164, v81
	v_lshl_add_u64 v[168:169], v[166:167], 0, v[82:83]
	s_waitcnt lgkmcnt(4)
	global_store_dwordx4 v[180:181], v[86:89], off offset:256
	v_cvt_pk_bf16_f32 v70, v70, v71
	v_cvt_pk_bf16_f32 v71, v72, v73
	v_cvt_pk_bf16_f32 v72, v66, v67
	v_cvt_pk_bf16_f32 v73, v68, v69
	ds_bpermute_b32 v70, v164, v70
	ds_bpermute_b32 v71, v164, v71
	ds_bpermute_b32 v72, v164, v72
	ds_bpermute_b32 v73, v164, v73
	v_lshl_add_u64 v[180:181], v[166:167], 0, v[82:83]
	s_waitcnt lgkmcnt(4)
	global_store_dwordx4 v[168:169], v[78:81], off
	s_mov_b64 s[28:29], 0x100000
	v_cvt_pk_bf16_f32 v62, v62, v63
	v_cvt_pk_bf16_f32 v63, v64, v65
	v_cvt_pk_bf16_f32 v64, v58, v59
	v_add_co_u32_e32 v58, vcc, s2, v148
	v_lshl_add_u64 v[66:67], v[148:149], 0, s[28:29]
	s_nop 0
	v_addc_co_u32_e32 v59, vcc, 0, v149, vcc
	v_cvt_pk_bf16_f32 v65, v60, v61
	ds_bpermute_b32 v62, v164, v62
	ds_bpermute_b32 v63, v164, v63
	ds_bpermute_b32 v64, v164, v64
	ds_bpermute_b32 v65, v164, v65
	v_lshl_add_u64 v[168:169], v[166:167], 0, v[58:59]
	s_waitcnt lgkmcnt(4)
	global_store_dwordx4 v[180:181], v[70:73], off offset:256
	v_cvt_pk_bf16_f32 v54, v54, v55
	v_cvt_pk_bf16_f32 v55, v56, v57
	v_cvt_pk_bf16_f32 v56, v50, v51
	v_cvt_pk_bf16_f32 v57, v52, v53
	ds_bpermute_b32 v54, v164, v54
	ds_bpermute_b32 v55, v164, v55
	ds_bpermute_b32 v56, v164, v56
	ds_bpermute_b32 v57, v164, v57
	v_lshl_add_u64 v[180:181], v[166:167], 0, v[66:67]
	s_waitcnt lgkmcnt(4)
	global_store_dwordx4 v[168:169], v[62:65], off
	v_cvt_pk_bf16_f32 v46, v46, v47
	v_cvt_pk_bf16_f32 v47, v48, v49
	v_cvt_pk_bf16_f32 v48, v42, v43
	v_add_co_u32_e32 v42, vcc, s55, v148
	v_lshl_add_u64 v[50:51], v[148:149], 0, s[8:9]
	s_nop 0
	v_addc_co_u32_e32 v43, vcc, 0, v149, vcc
	v_cvt_pk_bf16_f32 v49, v44, v45
	ds_bpermute_b32 v46, v164, v46
	ds_bpermute_b32 v47, v164, v47
	ds_bpermute_b32 v48, v164, v48
	ds_bpermute_b32 v49, v164, v49
	v_lshl_add_u64 v[168:169], v[166:167], 0, v[42:43]
	s_waitcnt lgkmcnt(4)
	global_store_dwordx4 v[180:181], v[54:57], off offset:256
	v_cvt_pk_bf16_f32 v38, v38, v39
	v_cvt_pk_bf16_f32 v39, v40, v41
	v_cvt_pk_bf16_f32 v40, v34, v35
	v_cvt_pk_bf16_f32 v41, v36, v37
	ds_bpermute_b32 v38, v164, v38
	ds_bpermute_b32 v39, v164, v39
	ds_bpermute_b32 v40, v164, v40
	ds_bpermute_b32 v41, v164, v41
	v_lshl_add_u64 v[180:181], v[166:167], 0, v[50:51]
	s_waitcnt lgkmcnt(4)
	global_store_dwordx4 v[168:169], v[46:49], off
	v_cvt_pk_bf16_f32 v30, v30, v31
	v_cvt_pk_bf16_f32 v31, v32, v33
	v_cvt_pk_bf16_f32 v32, v26, v27
	v_add_co_u32_e32 v26, vcc, s56, v148
	v_lshl_add_u64 v[34:35], v[148:149], 0, s[10:11]
	s_nop 0
	v_addc_co_u32_e32 v27, vcc, 0, v149, vcc
	v_cvt_pk_bf16_f32 v33, v28, v29
	ds_bpermute_b32 v30, v164, v30
	ds_bpermute_b32 v31, v164, v31
	ds_bpermute_b32 v32, v164, v32
	ds_bpermute_b32 v33, v164, v33
	v_lshl_add_u64 v[168:169], v[166:167], 0, v[26:27]
	s_waitcnt lgkmcnt(4)
	global_store_dwordx4 v[180:181], v[38:41], off offset:256
	v_cvt_pk_bf16_f32 v22, v22, v23
	v_cvt_pk_bf16_f32 v23, v24, v25
	v_cvt_pk_bf16_f32 v24, v18, v19
	v_cvt_pk_bf16_f32 v25, v20, v21
	ds_bpermute_b32 v22, v164, v22
	ds_bpermute_b32 v23, v164, v23
	ds_bpermute_b32 v24, v164, v24
	ds_bpermute_b32 v25, v164, v25
	v_lshl_add_u64 v[180:181], v[166:167], 0, v[34:35]
	s_waitcnt lgkmcnt(4)
	global_store_dwordx4 v[168:169], v[30:33], off
	v_cvt_pk_bf16_f32 v14, v14, v15
	v_cvt_pk_bf16_f32 v15, v16, v17
	v_cvt_pk_bf16_f32 v16, v10, v11
	v_add_co_u32_e32 v10, vcc, s57, v148
	v_lshl_add_u64 v[18:19], v[148:149], 0, s[12:13]
	s_nop 0
	v_addc_co_u32_e32 v11, vcc, 0, v149, vcc
	v_cvt_pk_bf16_f32 v17, v12, v13
	ds_bpermute_b32 v14, v164, v14
	ds_bpermute_b32 v15, v164, v15
	ds_bpermute_b32 v16, v164, v16
	ds_bpermute_b32 v17, v164, v17
	v_lshl_add_u64 v[168:169], v[166:167], 0, v[10:11]
	s_waitcnt lgkmcnt(4)
	global_store_dwordx4 v[180:181], v[22:25], off offset:256
	v_cvt_pk_bf16_f32 v6, v6, v7
	v_cvt_pk_bf16_f32 v7, v8, v9
	v_cvt_pk_bf16_f32 v8, v2, v3
	v_cvt_pk_bf16_f32 v9, v4, v5
	ds_bpermute_b32 v6, v164, v6
	ds_bpermute_b32 v7, v164, v7
	ds_bpermute_b32 v8, v164, v8
	ds_bpermute_b32 v9, v164, v9
	v_lshl_add_u64 v[180:181], v[166:167], 0, v[18:19]
	s_waitcnt lgkmcnt(4)
	global_store_dwordx4 v[168:169], v[14:17], off
	s_waitcnt lgkmcnt(0)
	global_store_dwordx4 v[180:181], v[6:9], off offset:256
	s_branch .LBB0_588

.LBB0_933:
	v_and_b32_e32 v165, 3, v174
	v_lshrrev_b32_e32 v170, 2, v174
	v_lshlrev_b32_e32 v164, 6, v165
	v_and_or_b32 v164, v174, 60, v164
	v_and_b32_e32 v171, 15, v174
	v_sub_u32_e32 v170, v170, v171
	v_lshrrev_b32_e32 v171, 4, v174
	v_sub_u32_e32 v165, v165, v171
	v_mul_i32_i24_e32 v170, 0x200, v170
	v_lshl_add_u32 v166, v165, 4, v170
	v_ashrrev_i32_e32 v167, 31, v166
	s_add_i32 s2, s2, -1
	s_lshl_b64 s[22:23], s[2:3], 17
	v_lshl_add_u64 v[150:151], v[142:143], 0, s[22:23]
	v_cvt_pk_bf16_f32 v154, v126, v127
	v_cvt_pk_bf16_f32 v155, v128, v129
	v_cvt_pk_bf16_f32 v156, v122, v123
	v_cvt_pk_bf16_f32 v157, v124, v125
	ds_bpermute_b32 v154, v164, v154
	ds_bpermute_b32 v155, v164, v155
	ds_bpermute_b32 v156, v164, v156
	ds_bpermute_b32 v157, v164, v157
	v_lshl_add_u64 v[168:169], v[166:167], 0, v[150:151]
	v_add_co_u32_e32 v158, vcc, s46, v150
	s_nop 0
	v_cvt_pk_bf16_f32 v176, v118, v119
	v_cvt_pk_bf16_f32 v177, v120, v121
	v_cvt_pk_bf16_f32 v178, v114, v115
	v_cvt_pk_bf16_f32 v179, v116, v117
	ds_bpermute_b32 v176, v164, v176
	ds_bpermute_b32 v177, v164, v177
	ds_bpermute_b32 v178, v164, v178
	ds_bpermute_b32 v179, v164, v179
	v_lshl_add_u64 v[180:181], v[166:167], 0, v[150:151]
	s_waitcnt lgkmcnt(4)
	global_store_dwordx4 v[168:169], v[154:157], off
	v_addc_co_u32_e32 v159, vcc, 0, v151, vcc
	s_nop 0
	v_cvt_pk_bf16_f32 v154, v110, v111
	v_cvt_pk_bf16_f32 v155, v112, v113
	v_cvt_pk_bf16_f32 v156, v106, v107
	v_cvt_pk_bf16_f32 v157, v108, v109
	ds_bpermute_b32 v154, v164, v154
	ds_bpermute_b32 v155, v164, v155
	ds_bpermute_b32 v156, v164, v156
	ds_bpermute_b32 v157, v164, v157
	v_lshl_add_u64 v[168:169], v[166:167], 0, v[158:159]
	s_waitcnt lgkmcnt(4)
	global_store_dwordx4 v[180:181], v[176:179], off offset:256
	s_mov_b64 s[22:23], 0
	s_nop 0
	v_cvt_pk_bf16_f32 v176, v102, v103
	v_cvt_pk_bf16_f32 v177, v104, v105
	v_cvt_pk_bf16_f32 v178, v98, v99
	v_cvt_pk_bf16_f32 v179, v100, v101
	ds_bpermute_b32 v176, v164, v176
	ds_bpermute_b32 v177, v164, v177
	ds_bpermute_b32 v178, v164, v178
	ds_bpermute_b32 v179, v164, v179
	v_lshl_add_u64 v[180:181], v[166:167], 0, v[158:159]
	s_waitcnt lgkmcnt(4)
	global_store_dwordx4 v[168:169], v[154:157], off
	v_add_co_u32_e32 v158, vcc, s47, v150
	s_nop 0
	v_cvt_pk_bf16_f32 v154, v94, v95
	v_cvt_pk_bf16_f32 v155, v96, v97
	v_cvt_pk_bf16_f32 v156, v90, v91
	v_cvt_pk_bf16_f32 v157, v92, v93
	s_nop 0
	v_addc_co_u32_e32 v159, vcc, 0, v151, vcc
	ds_bpermute_b32 v154, v164, v154
	ds_bpermute_b32 v155, v164, v155
	ds_bpermute_b32 v156, v164, v156
	ds_bpermute_b32 v157, v164, v157
	v_lshl_add_u64 v[168:169], v[166:167], 0, v[158:159]
	s_waitcnt lgkmcnt(4)
	global_store_dwordx4 v[180:181], v[176:179], off offset:256
	s_nop 1
	v_cvt_pk_bf16_f32 v176, v86, v87
	v_cvt_pk_bf16_f32 v177, v88, v89
	v_cvt_pk_bf16_f32 v178, v82, v83
	v_cvt_pk_bf16_f32 v179, v84, v85
	ds_bpermute_b32 v176, v164, v176
	ds_bpermute_b32 v177, v164, v177
	ds_bpermute_b32 v178, v164, v178
	ds_bpermute_b32 v179, v164, v179
	v_lshl_add_u64 v[180:181], v[166:167], 0, v[158:159]
	s_waitcnt lgkmcnt(4)
	global_store_dwordx4 v[168:169], v[154:157], off
	v_add_co_u32_e32 v158, vcc, s48, v150
	s_nop 0
	v_cvt_pk_bf16_f32 v154, v78, v79
	v_cvt_pk_bf16_f32 v155, v80, v81
	v_cvt_pk_bf16_f32 v156, v74, v75
	v_cvt_pk_bf16_f32 v157, v76, v77
	s_nop 0
	v_addc_co_u32_e32 v159, vcc, 0, v151, vcc
	ds_bpermute_b32 v154, v164, v154
	ds_bpermute_b32 v155, v164, v155
	ds_bpermute_b32 v156, v164, v156
	ds_bpermute_b32 v157, v164, v157
	v_lshl_add_u64 v[168:169], v[166:167], 0, v[158:159]
	s_waitcnt lgkmcnt(4)
	global_store_dwordx4 v[180:181], v[176:179], off offset:256
	s_nop 1
	v_cvt_pk_bf16_f32 v176, v70, v71
	v_cvt_pk_bf16_f32 v177, v72, v73
	v_cvt_pk_bf16_f32 v178, v66, v67
	v_cvt_pk_bf16_f32 v179, v68, v69
	ds_bpermute_b32 v176, v164, v176
	ds_bpermute_b32 v177, v164, v177
	ds_bpermute_b32 v178, v164, v178
	ds_bpermute_b32 v179, v164, v179
	v_lshl_add_u64 v[180:181], v[166:167], 0, v[158:159]
	s_waitcnt lgkmcnt(4)
	global_store_dwordx4 v[168:169], v[154:157], off
	v_add_co_u32_e32 v158, vcc, s42, v150
	s_nop 0
	v_cvt_pk_bf16_f32 v154, v62, v63
	v_cvt_pk_bf16_f32 v155, v64, v65
	v_cvt_pk_bf16_f32 v156, v58, v59
	v_cvt_pk_bf16_f32 v157, v60, v61
	s_nop 0
	v_addc_co_u32_e32 v159, vcc, 0, v151, vcc
	ds_bpermute_b32 v154, v164, v154
	ds_bpermute_b32 v155, v164, v155
	ds_bpermute_b32 v156, v164, v156
	ds_bpermute_b32 v157, v164, v157
	v_lshl_add_u64 v[168:169], v[166:167], 0, v[158:159]
	s_waitcnt lgkmcnt(4)
	global_store_dwordx4 v[180:181], v[176:179], off offset:256
	s_nop 1
	v_cvt_pk_bf16_f32 v176, v54, v55
	v_cvt_pk_bf16_f32 v177, v56, v57
	v_cvt_pk_bf16_f32 v178, v50, v51
	v_cvt_pk_bf16_f32 v179, v52, v53
	ds_bpermute_b32 v176, v164, v176
	ds_bpermute_b32 v177, v164, v177
	ds_bpermute_b32 v178, v164, v178
	ds_bpermute_b32 v179, v164, v179
	v_lshl_add_u64 v[180:181], v[166:167], 0, v[158:159]
	s_waitcnt lgkmcnt(4)
	global_store_dwordx4 v[168:169], v[154:157], off
	v_add_co_u32_e32 v158, vcc, s43, v150
	s_nop 0
	v_cvt_pk_bf16_f32 v154, v46, v47
	v_cvt_pk_bf16_f32 v155, v48, v49
	v_cvt_pk_bf16_f32 v156, v42, v43
	v_cvt_pk_bf16_f32 v157, v44, v45
	s_nop 0
	v_addc_co_u32_e32 v159, vcc, 0, v151, vcc
	ds_bpermute_b32 v154, v164, v154
	ds_bpermute_b32 v155, v164, v155
	ds_bpermute_b32 v156, v164, v156
	ds_bpermute_b32 v157, v164, v157
	v_lshl_add_u64 v[168:169], v[166:167], 0, v[158:159]
	s_waitcnt lgkmcnt(4)
	global_store_dwordx4 v[180:181], v[176:179], off offset:256
	s_nop 1
	v_cvt_pk_bf16_f32 v176, v38, v39
	v_cvt_pk_bf16_f32 v177, v40, v41
	v_cvt_pk_bf16_f32 v178, v34, v35
	v_cvt_pk_bf16_f32 v179, v36, v37
	ds_bpermute_b32 v176, v164, v176
	ds_bpermute_b32 v177, v164, v177
	ds_bpermute_b32 v178, v164, v178
	ds_bpermute_b32 v179, v164, v179
	v_lshl_add_u64 v[180:181], v[166:167], 0, v[158:159]
	s_waitcnt lgkmcnt(4)
	global_store_dwordx4 v[168:169], v[154:157], off
	v_add_co_u32_e32 v158, vcc, s44, v150
	s_nop 0
	v_cvt_pk_bf16_f32 v154, v30, v31
	v_cvt_pk_bf16_f32 v155, v32, v33
	v_cvt_pk_bf16_f32 v156, v26, v27
	v_cvt_pk_bf16_f32 v157, v28, v29
	s_nop 0
	v_addc_co_u32_e32 v159, vcc, 0, v151, vcc
	ds_bpermute_b32 v154, v164, v154
	ds_bpermute_b32 v155, v164, v155
	ds_bpermute_b32 v156, v164, v156
	ds_bpermute_b32 v157, v164, v157
	v_lshl_add_u64 v[168:169], v[166:167], 0, v[158:159]
	s_waitcnt lgkmcnt(4)
	global_store_dwordx4 v[180:181], v[176:179], off offset:256
	v_add_co_u32_e32 v150, vcc, s45, v150
	s_nop 0
	v_cvt_pk_bf16_f32 v176, v22, v23
	v_cvt_pk_bf16_f32 v177, v24, v25
	v_cvt_pk_bf16_f32 v178, v18, v19
	v_cvt_pk_bf16_f32 v179, v20, v21
	ds_bpermute_b32 v176, v164, v176
	ds_bpermute_b32 v177, v164, v177
	ds_bpermute_b32 v178, v164, v178
	ds_bpermute_b32 v179, v164, v179
	v_lshl_add_u64 v[180:181], v[166:167], 0, v[158:159]
	s_waitcnt lgkmcnt(4)
	global_store_dwordx4 v[168:169], v[154:157], off
	v_addc_co_u32_e32 v151, vcc, 0, v151, vcc
	s_nop 0
	v_cvt_pk_bf16_f32 v154, v14, v15
	v_cvt_pk_bf16_f32 v155, v16, v17
	v_cvt_pk_bf16_f32 v156, v10, v11
	v_cvt_pk_bf16_f32 v157, v12, v13
	ds_bpermute_b32 v154, v164, v154
	ds_bpermute_b32 v155, v164, v155
	ds_bpermute_b32 v156, v164, v156
	ds_bpermute_b32 v157, v164, v157
	v_lshl_add_u64 v[168:169], v[166:167], 0, v[150:151]
	s_waitcnt lgkmcnt(4)
	global_store_dwordx4 v[180:181], v[176:179], off offset:256
	s_nop 1
	v_cvt_pk_bf16_f32 v176, v6, v7
	v_cvt_pk_bf16_f32 v177, v8, v9
	v_cvt_pk_bf16_f32 v178, v2, v3
	v_cvt_pk_bf16_f32 v179, v4, v5
	ds_bpermute_b32 v176, v164, v176
	ds_bpermute_b32 v177, v164, v177
	ds_bpermute_b32 v178, v164, v178
	ds_bpermute_b32 v179, v164, v179
	v_lshl_add_u64 v[180:181], v[166:167], 0, v[150:151]
	s_waitcnt lgkmcnt(4)
	global_store_dwordx4 v[168:169], v[154:157], off
	s_waitcnt lgkmcnt(0)
	global_store_dwordx4 v[180:181], v[176:179], off offset:256
.LBB0_934:
	s_andn2_b64 vcc, exec, s[22:23]
	s_cbranch_vccnz .LBB0_924
	v_and_b32_e32 v165, 3, v174
	v_lshrrev_b32_e32 v170, 2, v174
	v_lshlrev_b32_e32 v164, 6, v165
	v_and_or_b32 v164, v174, 60, v164
	v_and_b32_e32 v171, 15, v174
	v_sub_u32_e32 v170, v170, v171
	v_lshrrev_b32_e32 v171, 4, v174
	v_sub_u32_e32 v165, v165, v171
	v_mul_i32_i24_e32 v170, 0x2000, v170
	v_lshl_add_u32 v166, v165, 4, v170
	v_ashrrev_i32_e32 v167, 31, v166
	v_lshl_add_u32 v154, s66, 8, v140
	v_lshl_or_b32 v150, s65, 8, v135
	v_ashrrev_i32_e32 v155, 31, v154
	v_ashrrev_i32_e32 v151, 31, v150
	v_lshlrev_b64 v[156:157], 13, v[154:155]
	v_lshl_add_u64 v[156:157], s[4:5], 0, v[156:157]
	v_lshlrev_b64 v[158:159], 1, v[150:151]
	v_lshl_add_u64 v[150:151], v[156:157], 0, v[158:159]
	v_cvt_pk_bf16_f32 v126, v126, v127
	v_cvt_pk_bf16_f32 v127, v128, v129
	v_cvt_pk_bf16_f32 v128, v122, v123
	v_cvt_pk_bf16_f32 v129, v124, v125
	ds_bpermute_b32 v126, v164, v126
	ds_bpermute_b32 v127, v164, v127
	ds_bpermute_b32 v128, v164, v128
	ds_bpermute_b32 v129, v164, v129
	v_lshl_add_u64 v[168:169], v[166:167], 0, v[150:151]
	v_cvt_pk_bf16_f32 v118, v118, v119
	v_cvt_pk_bf16_f32 v119, v120, v121
	v_cvt_pk_bf16_f32 v120, v114, v115
	v_or_b32_e32 v114, 16, v154
	v_ashrrev_i32_e32 v115, 31, v114
	v_lshlrev_b64 v[114:115], 13, v[114:115]
	v_lshl_add_u64 v[114:115], s[4:5], 0, v[114:115]
	v_lshl_add_u64 v[114:115], v[114:115], 0, v[158:159]
	v_cvt_pk_bf16_f32 v121, v116, v117
	ds_bpermute_b32 v118, v164, v118
	ds_bpermute_b32 v119, v164, v119
	ds_bpermute_b32 v120, v164, v120
	ds_bpermute_b32 v121, v164, v121
	v_lshl_add_u64 v[180:181], v[166:167], 0, v[150:151]
	s_waitcnt lgkmcnt(4)
	global_store_dwordx4 v[168:169], v[126:129], off
	v_cvt_pk_bf16_f32 v110, v110, v111
	v_cvt_pk_bf16_f32 v111, v112, v113
	v_cvt_pk_bf16_f32 v112, v106, v107
	v_cvt_pk_bf16_f32 v113, v108, v109
	ds_bpermute_b32 v110, v164, v110
	ds_bpermute_b32 v111, v164, v111
	ds_bpermute_b32 v112, v164, v112
	ds_bpermute_b32 v113, v164, v113
	v_lshl_add_u64 v[168:169], v[166:167], 0, v[114:115]
	s_waitcnt lgkmcnt(4)
	global_store_dwordx4 v[180:181], v[118:121], off offset:256
	v_cvt_pk_bf16_f32 v102, v102, v103
	v_cvt_pk_bf16_f32 v103, v104, v105
	v_cvt_pk_bf16_f32 v104, v98, v99
	v_or_b32_e32 v98, 32, v154
	v_ashrrev_i32_e32 v99, 31, v98
	v_lshlrev_b64 v[98:99], 13, v[98:99]
	v_lshl_add_u64 v[98:99], s[4:5], 0, v[98:99]
	v_lshl_add_u64 v[98:99], v[98:99], 0, v[158:159]
	v_cvt_pk_bf16_f32 v105, v100, v101
	ds_bpermute_b32 v102, v164, v102
	ds_bpermute_b32 v103, v164, v103
	ds_bpermute_b32 v104, v164, v104
	ds_bpermute_b32 v105, v164, v105
	v_lshl_add_u64 v[180:181], v[166:167], 0, v[114:115]
	s_waitcnt lgkmcnt(4)
	global_store_dwordx4 v[168:169], v[110:113], off
	v_cvt_pk_bf16_f32 v94, v94, v95
	v_cvt_pk_bf16_f32 v95, v96, v97
	v_cvt_pk_bf16_f32 v96, v90, v91
	v_cvt_pk_bf16_f32 v97, v92, v93
	ds_bpermute_b32 v94, v164, v94
	ds_bpermute_b32 v95, v164, v95
	ds_bpermute_b32 v96, v164, v96
	ds_bpermute_b32 v97, v164, v97
	v_lshl_add_u64 v[168:169], v[166:167], 0, v[98:99]
	s_waitcnt lgkmcnt(4)
	global_store_dwordx4 v[180:181], v[102:105], off offset:256
	v_cvt_pk_bf16_f32 v86, v86, v87
	v_cvt_pk_bf16_f32 v87, v88, v89
	v_cvt_pk_bf16_f32 v88, v82, v83
	v_or_b32_e32 v82, 48, v154
	v_ashrrev_i32_e32 v83, 31, v82
	v_lshlrev_b64 v[82:83], 13, v[82:83]
	v_lshl_add_u64 v[82:83], s[4:5], 0, v[82:83]
	v_lshl_add_u64 v[82:83], v[82:83], 0, v[158:159]
	v_cvt_pk_bf16_f32 v89, v84, v85
	ds_bpermute_b32 v86, v164, v86
	ds_bpermute_b32 v87, v164, v87
	ds_bpermute_b32 v88, v164, v88
	ds_bpermute_b32 v89, v164, v89
	v_lshl_add_u64 v[180:181], v[166:167], 0, v[98:99]
	s_waitcnt lgkmcnt(4)
	global_store_dwordx4 v[168:169], v[94:97], off
	v_cvt_pk_bf16_f32 v78, v78, v79
	v_cvt_pk_bf16_f32 v79, v80, v81
	v_cvt_pk_bf16_f32 v80, v74, v75
	v_cvt_pk_bf16_f32 v81, v76, v77
	ds_bpermute_b32 v78, v164, v78
	ds_bpermute_b32 v79, v164, v79
	ds_bpermute_b32 v80, v164, v80
	ds_bpermute_b32 v81, v164, v81
	v_lshl_add_u64 v[168:169], v[166:167], 0, v[82:83]
	s_waitcnt lgkmcnt(4)
	global_store_dwordx4 v[180:181], v[86:89], off offset:256
	v_cvt_pk_bf16_f32 v70, v70, v71
	v_cvt_pk_bf16_f32 v71, v72, v73
	v_cvt_pk_bf16_f32 v72, v66, v67
	v_cvt_pk_bf16_f32 v73, v68, v69
	ds_bpermute_b32 v70, v164, v70
	ds_bpermute_b32 v71, v164, v71
	ds_bpermute_b32 v72, v164, v72
	ds_bpermute_b32 v73, v164, v73
	v_lshl_add_u64 v[180:181], v[166:167], 0, v[82:83]
	s_waitcnt lgkmcnt(4)
	global_store_dwordx4 v[168:169], v[78:81], off
	v_cvt_pk_bf16_f32 v62, v62, v63
	v_cvt_pk_bf16_f32 v63, v64, v65
	v_cvt_pk_bf16_f32 v64, v58, v59
	v_add_co_u32_e32 v58, vcc, s59, v150
	v_lshl_add_u64 v[66:67], v[150:151], 0, s[8:9]
	s_nop 0
	v_addc_co_u32_e32 v59, vcc, 0, v151, vcc
	v_cvt_pk_bf16_f32 v65, v60, v61
	ds_bpermute_b32 v62, v164, v62
	ds_bpermute_b32 v63, v164, v63
	ds_bpermute_b32 v64, v164, v64
	ds_bpermute_b32 v65, v164, v65
	v_lshl_add_u64 v[168:169], v[166:167], 0, v[58:59]
	s_waitcnt lgkmcnt(4)
	global_store_dwordx4 v[180:181], v[70:73], off offset:256
	v_cvt_pk_bf16_f32 v54, v54, v55
	v_cvt_pk_bf16_f32 v55, v56, v57
	v_cvt_pk_bf16_f32 v56, v50, v51
	v_cvt_pk_bf16_f32 v57, v52, v53
	ds_bpermute_b32 v54, v164, v54
	ds_bpermute_b32 v55, v164, v55
	ds_bpermute_b32 v56, v164, v56
	ds_bpermute_b32 v57, v164, v57
	v_lshl_add_u64 v[180:181], v[166:167], 0, v[66:67]
	s_waitcnt lgkmcnt(4)
	global_store_dwordx4 v[168:169], v[62:65], off
	v_cvt_pk_bf16_f32 v46, v46, v47
	v_cvt_pk_bf16_f32 v47, v48, v49
	v_cvt_pk_bf16_f32 v48, v42, v43
	v_add_co_u32_e32 v42, vcc, s60, v150
	v_lshl_add_u64 v[50:51], v[150:151], 0, s[10:11]
	s_nop 0
	v_addc_co_u32_e32 v43, vcc, 0, v151, vcc
	v_cvt_pk_bf16_f32 v49, v44, v45
	ds_bpermute_b32 v46, v164, v46
	ds_bpermute_b32 v47, v164, v47
	ds_bpermute_b32 v48, v164, v48
	ds_bpermute_b32 v49, v164, v49
	v_lshl_add_u64 v[168:169], v[166:167], 0, v[42:43]
	s_waitcnt lgkmcnt(4)
	global_store_dwordx4 v[180:181], v[54:57], off offset:256
	v_cvt_pk_bf16_f32 v38, v38, v39
	v_cvt_pk_bf16_f32 v39, v40, v41
	v_cvt_pk_bf16_f32 v40, v34, v35
	v_cvt_pk_bf16_f32 v41, v36, v37
	ds_bpermute_b32 v38, v164, v38
	ds_bpermute_b32 v39, v164, v39
	ds_bpermute_b32 v40, v164, v40
	ds_bpermute_b32 v41, v164, v41
	v_lshl_add_u64 v[180:181], v[166:167], 0, v[50:51]
	s_waitcnt lgkmcnt(4)
	global_store_dwordx4 v[168:169], v[46:49], off
	v_cvt_pk_bf16_f32 v30, v30, v31
	v_cvt_pk_bf16_f32 v31, v32, v33
	v_cvt_pk_bf16_f32 v32, v26, v27
	v_add_co_u32_e32 v26, vcc, s61, v150
	v_lshl_add_u64 v[34:35], v[150:151], 0, s[12:13]
	s_nop 0
	v_addc_co_u32_e32 v27, vcc, 0, v151, vcc
	v_cvt_pk_bf16_f32 v33, v28, v29
	ds_bpermute_b32 v30, v164, v30
	ds_bpermute_b32 v31, v164, v31
	ds_bpermute_b32 v32, v164, v32
	ds_bpermute_b32 v33, v164, v33
	v_lshl_add_u64 v[168:169], v[166:167], 0, v[26:27]
	s_waitcnt lgkmcnt(4)
	global_store_dwordx4 v[180:181], v[38:41], off offset:256
	v_cvt_pk_bf16_f32 v22, v22, v23
	v_cvt_pk_bf16_f32 v23, v24, v25
	v_cvt_pk_bf16_f32 v24, v18, v19
	v_cvt_pk_bf16_f32 v25, v20, v21
	ds_bpermute_b32 v22, v164, v22
	ds_bpermute_b32 v23, v164, v23
	ds_bpermute_b32 v24, v164, v24
	ds_bpermute_b32 v25, v164, v25
	v_lshl_add_u64 v[180:181], v[166:167], 0, v[34:35]
	s_waitcnt lgkmcnt(4)
	global_store_dwordx4 v[168:169], v[30:33], off
	v_cvt_pk_bf16_f32 v14, v14, v15
	v_cvt_pk_bf16_f32 v15, v16, v17
	v_cvt_pk_bf16_f32 v16, v10, v11
	v_add_co_u32_e32 v10, vcc, s62, v150
	v_lshl_add_u64 v[18:19], v[150:151], 0, s[14:15]
	s_nop 0
	v_addc_co_u32_e32 v11, vcc, 0, v151, vcc
	v_cvt_pk_bf16_f32 v17, v12, v13
	ds_bpermute_b32 v14, v164, v14
	ds_bpermute_b32 v15, v164, v15
	ds_bpermute_b32 v16, v164, v16
	ds_bpermute_b32 v17, v164, v17
	v_lshl_add_u64 v[168:169], v[166:167], 0, v[10:11]
	s_waitcnt lgkmcnt(4)
	global_store_dwordx4 v[180:181], v[22:25], off offset:256
	v_cvt_pk_bf16_f32 v6, v6, v7
	v_cvt_pk_bf16_f32 v7, v8, v9
	v_cvt_pk_bf16_f32 v8, v2, v3
	v_cvt_pk_bf16_f32 v9, v4, v5
	ds_bpermute_b32 v6, v164, v6
	ds_bpermute_b32 v7, v164, v7
	ds_bpermute_b32 v8, v164, v8
	ds_bpermute_b32 v9, v164, v9
	v_lshl_add_u64 v[180:181], v[166:167], 0, v[18:19]
	s_waitcnt lgkmcnt(4)
	global_store_dwordx4 v[168:169], v[14:17], off
	s_waitcnt lgkmcnt(0)
	global_store_dwordx4 v[180:181], v[6:9], off offset:256
	s_branch .LBB0_924
